# cache f32->bf16 conversion loop: two items (4 loads per lane) in flight per trip
# speedup vs baseline: 1.0064x; 1.0064x over previous
.LBB0_1591:
	s_load_dwordx2 s[10:11], s[20:21], 0x0
	s_add_u32 s6, s58, s6
	v_mov_b32_e32 v0, v249
	s_addc_u32 s7, s59, s7
	s_ashr_i32 s5, s4, 31
	v_lshlrev_b32_e32 v2, 3, v0
	s_lshl_b64 s[4:5], s[4:5], 12
	v_ashrrev_i32_e32 v3, 31, v2
	v_lshl_add_u64 v[10:11], s[4:5], 0, v[2:3]
	s_waitcnt lgkmcnt(0)
	v_lshl_add_u64 v[6:7], v[10:11], 2, s[10:11]
	global_load_dwordx4 v[2:5], v[6:7], off
	s_nop 0
	global_load_dwordx4 v[6:9], v[6:7], off offset:16
	s_add_i32 s0, s0, s97
	v_lshl_add_u64 v[10:11], v[10:11], 1, s[6:7]
	s_cmpk_gt_i32 s0, 0xc9f
	s_cbranch_scc1 .Lcv_last1

.Lcv_body2:
	s_load_dwordx2 s[10:11], s[20:21], 0x0
	s_add_u32 s6, s58, s6
	v_mov_b32_e32 v162, v249
	s_addc_u32 s7, s59, s7
	s_ashr_i32 s5, s4, 31
	v_lshlrev_b32_e32 v160, 3, v162
	s_lshl_b64 s[4:5], s[4:5], 12
	v_ashrrev_i32_e32 v161, 31, v160
	v_lshl_add_u64 v[158:159], s[4:5], 0, v[160:161]
	s_waitcnt lgkmcnt(0)
	v_lshl_add_u64 v[152:153], v[158:159], 2, s[10:11]
	global_load_dwordx4 v[148:151], v[152:153], off
	s_nop 0
	global_load_dwordx4 v[152:155], v[152:153], off offset:16
	s_add_i32 s0, s0, s97
	v_lshl_add_u64 v[158:159], v[158:159], 1, s[6:7]
	s_waitcnt vmcnt(2)
	v_cvt_pk_bf16_f32 v2, v2, v3
	v_cvt_pk_bf16_f32 v3, v4, v5
	v_cvt_pk_bf16_f32 v4, v6, v7
	v_cvt_pk_bf16_f32 v5, v8, v9
	global_store_dwordx4 v[10:11], v[2:5], off
	s_waitcnt vmcnt(1)
	v_cvt_pk_bf16_f32 v148, v148, v149
	v_cvt_pk_bf16_f32 v149, v150, v151
	v_cvt_pk_bf16_f32 v150, v152, v153
	v_cvt_pk_bf16_f32 v151, v154, v155
	global_store_dwordx4 v[158:159], v[148:151], off
	s_cmpk_gt_i32 s0, 0xc9f
	s_cbranch_scc0 .LBB0_1592
	s_branch .Lcv_exit
.Lcv_last1:
	s_waitcnt vmcnt(0)
	v_cvt_pk_bf16_f32 v2, v2, v3
	v_cvt_pk_bf16_f32 v3, v4, v5
	v_cvt_pk_bf16_f32 v4, v6, v7
	v_cvt_pk_bf16_f32 v5, v8, v9
	global_store_dwordx4 v[10:11], v[2:5], off
